# h1 a_lr tail: H rows re-read by LDS-DMA as contiguous 512-B row windows into a per-wave LDS tile, A fragments by ds_read_b128 (direct HBM->LDS strategy)
# baseline (speedup 1.0000x reference)
; __device__ __forceinline__ v4u pack8(const float (&f)[8]) { v4u w; w.x = pk2(f[0], f[1]); w.y = pk2(f[2], f[3]); w.z = pk2(f[4], f[5]); w.w = pk2(f[6], f[7]); return w; }
; __device__ __forceinline__ void phase_h1(const Args& a, int lane, int wave) {
;     ...
;         for (int r = 0; r < 16; ++r) {
;             { const float* xr = a.in[I_X] + (size_t)(m0 + (r < 15 ? r + 1 : r)) * D + 8 * lane;
; #pragma unroll
;               for (int j = 0; j < 4; ++j) { vn[j][0] = *(const f32x4*)(xr + 512 * j); vn[j][1] = *(const f32x4*)(xr + 512 * j + 4); } }
;             float ss = 0.f;
; #pragma unroll
;             for (int j = 0; j < 4; ++j)
; #pragma unroll
;                 for (int q = 0; q < 2; ++q) ss += (v[j][q].x * v[j][q].x + v[j][q].y * v[j][q].y) + (v[j][q].z * v[j][q].z + v[j][q].w * v[j][q].w);
;             const float rstd = rsqrtf(wave_sum(ss) * (1.0f / D) + EPS);
;             bf16* hr = H + (size_t)(m0 + r) * D + 8 * lane;
; #pragma unroll
;             for (int j = 0; j < 4; ++j) { float o[8];
; #pragma unroll
;                 for (int e = 0; e < 8; ++e) o[e] = v[j][e >> 2][e & 3] * rstd * A[j][e] + B[j][e];
;                 *(v4u*)(hr + 512 * j) = pack8(o); }
; #pragma unroll
;             for (int j = 0; j < 4; ++j) { v[j][0] = vn[j][0]; v[j][1] = vn[j][1]; }
.LBB0_147:
	v_lshl_add_u64 v[80:81], v[156:157], 0, s[22:23]
	s_waitcnt vmcnt(14)
	v_mov_b32_e32 v84, v37
	v_mov_b32_e32 v85, v33
	v_mov_b32_e32 v88, v39
	v_mov_b32_e32 v89, v35
	s_waitcnt vmcnt(12)
	v_pk_mul_f32 v[64:65], v[46:47], v[46:47]
	v_pk_mul_f32 v[90:91], v[44:45], v[44:45]
	s_waitcnt vmcnt(11)
	v_mul_f32_e32 v93, v54, v54
	v_mul_f32_e32 v95, v55, v55
	v_mul_f32_e32 v92, v41, v41
	v_mul_f32_e32 v94, v43, v43
	s_waitcnt vmcnt(10)
	v_pk_mul_f32 v[66:67], v[50:51], v[50:51]
	v_pk_mul_f32 v[168:169], v[48:49], v[48:49]
	v_add_co_u32_e32 v182, vcc, s38, v80
	v_mov_b32_e32 v82, v36
	v_mov_b32_e32 v83, v32
	v_mov_b32_e32 v86, v38
	v_mov_b32_e32 v87, v34
	global_load_dwordx4 v[68:71], v[80:81], off offset:16
	global_load_dwordx4 v[76:79], v[80:81], off
	v_pk_mov_b32 v[176:177], v[90:91], v[64:65] op_sel:[1,0]
	v_mov_b32_e32 v91, v65
	v_pk_mov_b32 v[178:179], v[168:169], v[66:67] op_sel:[1,0]
	v_mov_b32_e32 v169, v67
	global_load_dwordx4 v[64:67], v[80:81], off offset:2064
	global_load_dwordx4 v[72:75], v[80:81], off offset:2048
	v_pk_mul_f32 v[84:85], v[84:85], v[84:85]
	v_lshl_add_u64 v[180:181], v[80:81], 0, s[14:15]
	v_pk_mul_f32 v[88:89], v[88:89], v[88:89]
	v_addc_co_u32_e32 v183, vcc, 0, v81, vcc
	v_lshl_add_u64 v[80:81], v[80:81], 0, s[16:17]
	v_pk_fma_f32 v[184:185], v[40:41], v[40:41], v[92:93] op_sel_hi:[1,1,0]
	v_pk_fma_f32 v[186:187], v[42:43], v[42:43], v[94:95] op_sel_hi:[1,1,0]
	v_pk_fma_f32 v[188:189], v[82:83], v[82:83], v[84:85]
	v_pk_fma_f32 v[190:191], v[86:87], v[86:87], v[88:89]
	v_pk_add_f32 v[176:177], v[176:177], v[90:91]
	v_mov_b32_e32 v185, v93
	v_mov_b32_e32 v187, v95
	global_load_dwordx4 v[88:91], v[180:181], off offset:16
	global_load_dwordx4 v[92:95], v[182:183], off
	s_nop 0
	global_load_dwordx4 v[80:83], v[80:81], off offset:16
	s_nop 0
	global_load_dwordx4 v[84:87], v[182:183], off offset:2048
	s_waitcnt vmcnt(9)
	v_mul_f32_e32 v170, v61, v61
	v_mul_f32_e32 v172, v63, v63
	s_waitcnt vmcnt(8)
	v_mul_f32_e32 v194, v58, v58
	v_mul_f32_e32 v195, v59, v59
	v_pk_fma_f32 v[170:171], v[60:61], v[60:61], v[170:171] op_sel_hi:[1,1,0]
	v_pk_fma_f32 v[172:173], v[62:63], v[62:63], v[172:173] op_sel_hi:[1,1,0]
	v_mov_b32_e32 v171, v194
	v_mov_b32_e32 v173, v195
	v_pk_add_f32 v[180:181], v[188:189], v[190:191]
	v_mul_f32_e32 v117, v52, v52
	v_mul_f32_e32 v167, v53, v53
	v_pk_add_f32 v[176:177], v[176:177], v[176:177] op_sel:[0,1] op_sel_hi:[1,0]
	v_pk_add_f32 v[170:171], v[170:171], v[172:173]
	v_pk_add_f32 v[172:173], v[180:181], v[180:181] op_sel:[0,1] op_sel_hi:[1,0]
	v_mov_b32_e32 v177, v167
	v_mov_b32_e32 v173, v117
	v_pk_add_f32 v[182:183], v[184:185], v[186:187]
	v_pk_add_f32 v[172:173], v[172:173], v[176:177]
	v_pk_add_f32 v[168:169], v[178:179], v[168:169]
	v_pk_add_f32 v[172:173], v[172:173], v[182:183]
	v_mul_f32_e32 v192, v56, v56
	v_mul_f32_e32 v193, v57, v57
	v_pk_add_f32 v[168:169], v[168:169], v[168:169] op_sel:[0,1] op_sel_hi:[1,0]
	v_pk_add_f32 v[172:173], v[172:173], v[172:173] op_sel:[0,1] op_sel_hi:[1,0]
	v_mov_b32_e32 v169, v193
	v_mov_b32_e32 v173, v192
	v_pk_add_f32 v[168:169], v[172:173], v[168:169]
	s_ashr_i32 s25, s24, 31
	v_pk_add_f32 v[168:169], v[168:169], v[170:171]
	s_lshl_b64 s[42:43], s[24:25], 12
	v_add_f32_e32 v117, v168, v169
	s_add_i32 s24, s24, 1
	v_lshl_add_u64 v[178:179], v[98:99], 0, s[42:43]
	s_add_u32 s22, s22, 0x2000
	s_addc_u32 s23, s23, 0
	s_waitcnt lgkmcnt(0)
	s_nop 1
	v_add_f32_dpp v117, v117, v117 quad_perm:[1,0,3,2] row_mask:0xf bank_mask:0xf
	s_cmp_eq_u32 s22, 0x1e000
	s_waitcnt lgkmcnt(0)
	s_nop 1
	v_add_f32_dpp v117, v117, v117 quad_perm:[2,3,0,1] row_mask:0xf bank_mask:0xf
	s_waitcnt lgkmcnt(0)
	s_nop 1
	v_add_f32_dpp v117, v117, v117 row_half_mirror row_mask:0xf bank_mask:0xf
	s_waitcnt lgkmcnt(0)
	s_nop 1
	v_add_f32_dpp v117, v117, v117 row_mirror row_mask:0xf bank_mask:0xf
	s_waitcnt lgkmcnt(0)
	s_nop 1
	v_add_f32_dpp v117, v117, v117 row_bcast:15 row_mask:0xa bank_mask:0xf
	s_waitcnt lgkmcnt(0)
	s_nop 1
	v_add_f32_dpp v117, v117, v117 row_bcast:31 row_mask:0xc bank_mask:0xf
	s_nop 0
	v_readlane_b32 s99, v117, 63
	s_nop 1
	v_mov_b32_e32 v117, s99
	v_fmamk_f32 v117, v117, 0x3a000000, v166
	v_mul_f32_e32 v167, 0x4b800000, v117
	v_cmp_gt_f32_e32 vcc, s39, v117
	s_nop 1
	v_cndmask_b32_e32 v117, v117, v167, vcc
	v_rsq_f32_e32 v117, v117
	s_nop 0
	v_mul_f32_e32 v167, 0x45800000, v117
	v_cndmask_b32_e32 v168, v117, v167, vcc
	v_pk_mul_f32 v[36:37], v[36:37], v[168:169] op_sel_hi:[1,0]
	v_pk_mul_f32 v[38:39], v[38:39], v[168:169] op_sel_hi:[1,0]
	v_pk_mul_f32 v[32:33], v[32:33], v[168:169] op_sel_hi:[1,0]
	v_pk_mul_f32 v[34:35], v[34:35], v[168:169] op_sel_hi:[1,0]
	v_pk_mul_f32 v[44:45], v[44:45], v[168:169] op_sel_hi:[1,0]
	v_pk_mul_f32 v[46:47], v[46:47], v[168:169] op_sel_hi:[1,0]
	v_pk_mul_f32 v[40:41], v[40:41], v[168:169] op_sel_hi:[1,0]
	v_pk_mul_f32 v[42:43], v[42:43], v[168:169] op_sel_hi:[1,0]
	v_pk_mul_f32 v[52:53], v[52:53], v[168:169] op_sel_hi:[1,0]
	v_pk_mul_f32 v[54:55], v[54:55], v[168:169] op_sel_hi:[1,0]
	v_pk_mul_f32 v[48:49], v[48:49], v[168:169] op_sel_hi:[1,0]
	v_pk_mul_f32 v[50:51], v[50:51], v[168:169] op_sel_hi:[1,0]
	v_pk_mul_f32 v[60:61], v[60:61], v[168:169] op_sel_hi:[1,0]
	v_pk_mul_f32 v[62:63], v[62:63], v[168:169] op_sel_hi:[1,0]
	v_pk_mul_f32 v[56:57], v[56:57], v[168:169] op_sel_hi:[1,0]
	v_pk_mul_f32 v[58:59], v[58:59], v[168:169] op_sel_hi:[1,0]
	v_pk_fma_f32 v[36:37], v[154:155], v[36:37], v[28:29]
	v_pk_fma_f32 v[38:39], v[152:153], v[38:39], v[30:31]
	v_pk_fma_f32 v[168:169], v[150:151], v[32:33], v[24:25]
	v_pk_fma_f32 v[170:171], v[148:149], v[34:35], v[26:27]
	v_pk_fma_f32 v[44:45], v[146:147], v[44:45], v[20:21]
	v_pk_fma_f32 v[46:47], v[144:145], v[46:47], v[22:23]
	v_pk_fma_f32 v[40:41], v[142:143], v[40:41], v[16:17]
	v_pk_fma_f32 v[42:43], v[140:141], v[42:43], v[18:19]
	v_pk_fma_f32 v[52:53], v[138:139], v[52:53], v[12:13]
	v_pk_fma_f32 v[54:55], v[136:137], v[54:55], v[14:15]
	v_pk_fma_f32 v[48:49], v[134:135], v[48:49], v[8:9]
	v_pk_fma_f32 v[50:51], v[132:133], v[50:51], v[10:11]
	v_pk_fma_f32 v[60:61], v[128:129], v[60:61], v[4:5]
	v_pk_fma_f32 v[62:63], v[126:127], v[62:63], v[6:7]
	v_pk_fma_f32 v[56:57], v[130:131], v[56:57], v[0:1]
	v_pk_fma_f32 v[58:59], v[124:125], v[58:59], v[2:3]
	v_cvt_pk_bf16_f32 v32, v36, v37
	v_cvt_pk_bf16_f32 v33, v38, v39
	v_cvt_pk_bf16_f32 v34, v168, v169
	v_cvt_pk_bf16_f32 v35, v170, v171
	v_cvt_pk_bf16_f32 v36, v44, v45
	v_cvt_pk_bf16_f32 v37, v46, v47
	v_cvt_pk_bf16_f32 v38, v40, v41
	v_cvt_pk_bf16_f32 v39, v42, v43
	v_cvt_pk_bf16_f32 v40, v52, v53
	v_cvt_pk_bf16_f32 v41, v54, v55
	v_cvt_pk_bf16_f32 v42, v48, v49
	v_cvt_pk_bf16_f32 v43, v50, v51
	v_cvt_pk_bf16_f32 v44, v60, v61
	v_cvt_pk_bf16_f32 v45, v62, v63
	v_cvt_pk_bf16_f32 v46, v56, v57
	v_cvt_pk_bf16_f32 v47, v58, v59
	global_store_dwordx4 v[178:179], v[32:35], off
	global_store_dwordx4 v[178:179], v[36:39], off offset:1024
	global_store_dwordx4 v[178:179], v[40:43], off offset:2048
	global_store_dwordx4 v[178:179], v[44:47], off offset:3072
	s_waitcnt vmcnt(10)
; __device__ __forceinline__ v4u pack8(const float (&f)[8]) { v4u w; w.x = pk2(f[0], f[1]); w.y = pk2(f[2], f[3]); w.z = pk2(f[4], f[5]); w.w = pk2(f[6], f[7]); return w; }
; __device__ __forceinline__ void phase_h1(const Args& a, int lane, int wave) {
;     ...
;         for (int r = 0; r < 16; ++r) {
;             { const float* xr = a.in[I_X] + (size_t)(m0 + (r < 15 ? r + 1 : r)) * D + 8 * lane;
; #pragma unroll
;               for (int j = 0; j < 4; ++j) { vn[j][0] = *(const f32x4*)(xr + 512 * j); vn[j][1] = *(const f32x4*)(xr + 512 * j + 4); } }
;             float ss = 0.f;
; #pragma unroll
;             for (int j = 0; j < 4; ++j)
; #pragma unroll
;                 for (int q = 0; q < 2; ++q) ss += (v[j][q].x * v[j][q].x + v[j][q].y * v[j][q].y) + (v[j][q].z * v[j][q].z + v[j][q].w * v[j][q].w);
;             const float rstd = rsqrtf(wave_sum(ss) * (1.0f / D) + EPS);
;             bf16* hr = H + (size_t)(m0 + r) * D + 8 * lane;
; #pragma unroll
;             for (int j = 0; j < 4; ++j) { float o[8];
; #pragma unroll
;                 for (int e = 0; e < 8; ++e) o[e] = v[j][e >> 2][e & 3] * rstd * A[j][e] + B[j][e];
;                 *(v4u*)(hr + 512 * j) = pack8(o); }
; #pragma unroll
;             for (int j = 0; j < 4; ++j) { v[j][0] = vn[j][0]; v[j][1] = vn[j][1]; }
;         }
;         asm volatile("s_waitcnt vmcnt(0)" ::: "memory");
	v_mov_b64_e32 v[36:37], v[76:77]
	v_mov_b64_e32 v[32:33], v[68:69]
	s_waitcnt vmcnt(8)
	v_mov_b64_e32 v[44:45], v[72:73]
	v_mov_b64_e32 v[40:41], v[64:65]
	s_waitcnt vmcnt(7)
	v_mov_b64_e32 v[48:49], v[88:89]
	s_waitcnt vmcnt(5)
	v_mov_b64_e32 v[56:57], v[80:81]
	v_mov_b64_e32 v[52:53], v[92:93]
	s_waitcnt vmcnt(4)
	v_mov_b64_e32 v[60:61], v[84:85]
	v_mov_b64_e32 v[38:39], v[78:79]
	v_mov_b64_e32 v[34:35], v[70:71]
	v_mov_b64_e32 v[46:47], v[74:75]
	v_mov_b64_e32 v[42:43], v[66:67]
	v_mov_b64_e32 v[50:51], v[90:91]
	v_mov_b64_e32 v[58:59], v[82:83]
	v_mov_b64_e32 v[54:55], v[94:95]
	v_mov_b64_e32 v[62:63], v[86:87]
	s_cbranch_scc0 .LBB0_147
	v_mov_b32_e32 v34, v77
	v_mov_b32_e32 v35, v69
	v_mov_b32_e32 v32, v76
	v_mov_b32_e32 v33, v68
	v_pk_mul_f32 v[34:35], v[34:35], v[34:35]
	v_mov_b32_e32 v36, v79
	v_mov_b32_e32 v37, v71
	v_pk_fma_f32 v[32:33], v[32:33], v[32:33], v[34:35]
	v_mov_b32_e32 v34, v78
	v_mov_b32_e32 v35, v70
	v_pk_mul_f32 v[36:37], v[36:37], v[36:37]
	s_or_b32 s22, s20, 15
	v_pk_fma_f32 v[34:35], v[34:35], v[34:35], v[36:37]
	v_pk_mul_f32 v[36:37], v[72:73], v[72:73]
	v_pk_add_f32 v[32:33], v[32:33], v[34:35]
	v_pk_mul_f32 v[34:35], v[74:75], v[74:75]
	v_pk_add_f32 v[32:33], v[32:33], v[32:33] op_sel:[0,1] op_sel_hi:[1,0]
	v_pk_mov_b32 v[38:39], v[36:37], v[34:35] op_sel:[1,0]
	v_mov_b32_e32 v37, v35
	v_pk_add_f32 v[34:35], v[38:39], v[36:37]
	v_mul_f32_e32 v36, v92, v92
	v_mul_f32_e32 v37, v93, v93
	v_pk_add_f32 v[34:35], v[34:35], v[34:35] op_sel:[0,1] op_sel_hi:[1,0]
	v_mov_b32_e32 v33, v36
	v_mov_b32_e32 v35, v37
	v_pk_add_f32 v[32:33], v[32:33], v[34:35]
	v_mul_f32_e32 v34, v65, v65
	v_mul_f32_e32 v36, v67, v67
	v_mul_f32_e32 v38, v94, v94
	v_mul_f32_e32 v39, v95, v95
	v_pk_fma_f32 v[34:35], v[64:65], v[64:65], v[34:35] op_sel_hi:[1,1,0]
	v_pk_fma_f32 v[36:37], v[66:67], v[66:67], v[36:37] op_sel_hi:[1,1,0]
	v_mov_b32_e32 v35, v38
	v_mov_b32_e32 v37, v39
	v_pk_add_f32 v[34:35], v[34:35], v[36:37]
	v_pk_mul_f32 v[36:37], v[88:89], v[88:89]
	v_pk_add_f32 v[32:33], v[32:33], v[34:35]
	v_pk_mul_f32 v[34:35], v[90:91], v[90:91]
	v_pk_add_f32 v[32:33], v[32:33], v[32:33] op_sel:[0,1] op_sel_hi:[1,0]
	v_pk_mov_b32 v[38:39], v[36:37], v[34:35] op_sel:[1,0]
	v_mov_b32_e32 v37, v35
	v_pk_add_f32 v[34:35], v[38:39], v[36:37]
	v_mul_f32_e32 v36, v80, v80
	v_mul_f32_e32 v37, v81, v81
	v_pk_add_f32 v[34:35], v[34:35], v[34:35] op_sel:[0,1] op_sel_hi:[1,0]
	v_mov_b32_e32 v33, v36
	v_mov_b32_e32 v35, v37
	v_pk_add_f32 v[32:33], v[32:33], v[34:35]
	v_mul_f32_e32 v34, v85, v85
	v_mul_f32_e32 v36, v87, v87
	v_mul_f32_e32 v38, v82, v82
	v_mul_f32_e32 v39, v83, v83
	v_pk_fma_f32 v[34:35], v[84:85], v[84:85], v[34:35] op_sel_hi:[1,1,0]
	v_pk_fma_f32 v[36:37], v[86:87], v[86:87], v[36:37] op_sel_hi:[1,1,0]
	v_mov_b32_e32 v35, v38
	v_mov_b32_e32 v37, v39
	v_pk_add_f32 v[34:35], v[34:35], v[36:37]
	s_ashr_i32 s23, s22, 31
	v_pk_add_f32 v[32:33], v[32:33], v[34:35]
	s_lshl_b64 s[22:23], s[22:23], 12
	v_add_f32_e32 v32, v32, v33
	v_lshl_add_u64 v[36:37], v[98:99], 0, s[22:23]
	v_ashrrev_i32_e32 v117, 31, v116
	s_mov_b32 s9, 8
	s_waitcnt lgkmcnt(0)
	s_nop 1
	v_add_f32_dpp v32, v32, v32 quad_perm:[1,0,3,2] row_mask:0xf bank_mask:0xf
	s_waitcnt lgkmcnt(0)
	s_nop 1
	v_add_f32_dpp v32, v32, v32 quad_perm:[2,3,0,1] row_mask:0xf bank_mask:0xf
	s_waitcnt lgkmcnt(0)
	s_nop 1
	v_add_f32_dpp v32, v32, v32 row_half_mirror row_mask:0xf bank_mask:0xf
	s_waitcnt lgkmcnt(0)
	s_nop 1
	v_add_f32_dpp v32, v32, v32 row_mirror row_mask:0xf bank_mask:0xf
	s_waitcnt lgkmcnt(0)
	s_nop 1
	v_add_f32_dpp v32, v32, v32 row_bcast:15 row_mask:0xa bank_mask:0xf
	s_waitcnt lgkmcnt(0)
	s_nop 1
	v_add_f32_dpp v32, v32, v32 row_bcast:31 row_mask:0xc bank_mask:0xf
	s_nop 0
	v_readlane_b32 s99, v32, 63
	s_nop 1
	v_mov_b32_e32 v32, s99
	v_fmamk_f32 v32, v32, 0x3a000000, v166
	v_mul_f32_e32 v33, 0x4b800000, v32
	v_cmp_gt_f32_e32 vcc, s39, v32
	s_nop 1
	v_cndmask_b32_e32 v32, v32, v33, vcc
	v_rsq_f32_e32 v34, v32
	v_lshlrev_b64 v[32:33], 12, v[116:117]
	v_lshl_add_u64 v[32:33], s[80:81], 0, v[32:33]
	v_mul_f32_e32 v35, 0x45800000, v34
	v_cndmask_b32_e32 v34, v34, v35, vcc
	v_pk_mul_f32 v[38:39], v[76:77], v[34:35] op_sel_hi:[1,0]
	s_nop 0
	v_pk_fma_f32 v[28:29], v[154:155], v[38:39], v[28:29]
	v_pk_mul_f32 v[38:39], v[78:79], v[34:35] op_sel_hi:[1,0]
	s_nop 0
	v_pk_fma_f32 v[30:31], v[152:153], v[38:39], v[30:31]
	v_pk_mul_f32 v[38:39], v[68:69], v[34:35] op_sel_hi:[1,0]
	s_nop 0
	v_pk_fma_f32 v[38:39], v[150:151], v[38:39], v[24:25]
	v_pk_mul_f32 v[24:25], v[70:71], v[34:35] op_sel_hi:[1,0]
	s_nop 0
	v_pk_fma_f32 v[40:41], v[148:149], v[24:25], v[26:27]
	v_cvt_pk_bf16_f32 v24, v28, v29
	v_cvt_pk_bf16_f32 v25, v30, v31
	v_cvt_pk_bf16_f32 v26, v38, v39
	v_cvt_pk_bf16_f32 v27, v40, v41
	global_store_dwordx4 v[36:37], v[24:27], off
	s_nop 1
	v_pk_mul_f32 v[24:25], v[72:73], v[34:35] op_sel_hi:[1,0]
	s_nop 0
	v_pk_fma_f32 v[20:21], v[146:147], v[24:25], v[20:21]
	v_pk_mul_f32 v[24:25], v[74:75], v[34:35] op_sel_hi:[1,0]
	s_nop 0
	v_pk_fma_f32 v[22:23], v[144:145], v[24:25], v[22:23]
	v_pk_mul_f32 v[24:25], v[64:65], v[34:35] op_sel_hi:[1,0]
	s_nop 0
	v_pk_fma_f32 v[24:25], v[142:143], v[24:25], v[16:17]
	v_pk_mul_f32 v[16:17], v[66:67], v[34:35] op_sel_hi:[1,0]
	s_nop 0
	v_pk_fma_f32 v[26:27], v[140:141], v[16:17], v[18:19]
	v_cvt_pk_bf16_f32 v16, v20, v21
	v_cvt_pk_bf16_f32 v17, v22, v23
	v_cvt_pk_bf16_f32 v18, v24, v25
	v_cvt_pk_bf16_f32 v19, v26, v27
	global_store_dwordx4 v[36:37], v[16:19], off offset:1024
	s_nop 1
	v_pk_mul_f32 v[16:17], v[92:93], v[34:35] op_sel_hi:[1,0]
	s_nop 0
	v_pk_fma_f32 v[12:13], v[138:139], v[16:17], v[12:13]
	v_pk_mul_f32 v[16:17], v[94:95], v[34:35] op_sel_hi:[1,0]
	s_nop 0
	v_pk_fma_f32 v[14:15], v[136:137], v[16:17], v[14:15]
	v_pk_mul_f32 v[16:17], v[88:89], v[34:35] op_sel_hi:[1,0]
	s_nop 0
	v_pk_fma_f32 v[16:17], v[134:135], v[16:17], v[8:9]
	v_pk_mul_f32 v[8:9], v[90:91], v[34:35] op_sel_hi:[1,0]
	s_nop 0
	v_pk_fma_f32 v[18:19], v[132:133], v[8:9], v[10:11]
	v_cvt_pk_bf16_f32 v8, v12, v13
	v_cvt_pk_bf16_f32 v9, v14, v15
	v_cvt_pk_bf16_f32 v10, v16, v17
	v_cvt_pk_bf16_f32 v11, v18, v19
	global_store_dwordx4 v[36:37], v[8:11], off offset:2048
	v_mov_b64_e32 v[14:15], v[112:113]
	s_nop 0
	v_pk_mul_f32 v[8:9], v[84:85], v[34:35] op_sel_hi:[1,0]
	s_nop 0
	v_pk_fma_f32 v[4:5], v[128:129], v[8:9], v[4:5]
	v_pk_mul_f32 v[8:9], v[86:87], v[34:35] op_sel_hi:[1,0]
	s_nop 0
	v_pk_fma_f32 v[6:7], v[126:127], v[8:9], v[6:7]
	v_pk_mul_f32 v[8:9], v[80:81], v[34:35] op_sel_hi:[1,0]
	s_nop 0
	v_pk_fma_f32 v[8:9], v[130:131], v[8:9], v[0:1]
	v_pk_mul_f32 v[0:1], v[82:83], v[34:35] op_sel_hi:[1,0]
	s_nop 0
	v_pk_fma_f32 v[10:11], v[124:125], v[0:1], v[2:3]
	v_cvt_pk_bf16_f32 v0, v4, v5
	v_cvt_pk_bf16_f32 v1, v6, v7
	v_cvt_pk_bf16_f32 v2, v8, v9
	v_cvt_pk_bf16_f32 v3, v10, v11
	global_store_dwordx4 v[36:37], v[0:3], off offset:3072
	s_waitcnt vmcnt(0)
; __device__ __forceinline__ void phase_h1(const Args& a, int lane, int wave) {
;     ...
;         { const int r16 = lane & 15, q4 = lane >> 4;
;           const bf16* hrow = H + (size_t)(m0 + r16) * D + 8 * q4; const bf16* wrow = (const bf16*)(a.ws + WS_WIN) + (size_t)(NIN + r16) * D + 8 * q4;
;           f32x4 acc0 = (f32x4){0.f, 0.f, 0.f, 0.f}, acc1 = acc0;
;           bf16x8 af[8], bf[8], an[8], bn[8];
; #pragma unroll
;           for (int i = 0; i < 8; ++i) { af[i] = *(const bf16x8*)(hrow + 32 * i); bf[i] = *(const bf16x8*)(wrow + 32 * i); }
;           for (int ks = 0; ks < 64; ks += 8) {
;               const int kn = ks + 8 < 64 ? ks + 8 : ks;
; #pragma unroll
;               for (int i = 0; i < 8; ++i) { an[i] = *(const bf16x8*)(hrow + 32 * (kn + i)); bn[i] = *(const bf16x8*)(wrow + 32 * (kn + i)); }
	v_mov_b64_e32 v[10:11], v[110:111]
	s_nop 0
	v_or_b32_e32 v0, s20, v158
	v_ashrrev_i32_e32 v1, 31, v0
	v_lshlrev_b64 v[0:1], 12, v[0:1]
	v_lshl_add_u64 v[8:9], v[100:101], 0, v[0:1]
	v_mov_b32_e32 v0, 0
	v_mov_b64_e32 v[12:13], v[8:9]
	v_mov_b32_e32 v1, v0
	v_mov_b32_e32 v2, v0
	v_mov_b32_e32 v3, v0
	v_mov_b32_e32 v4, v0
	v_mov_b32_e32 v5, v0
	v_mov_b32_e32 v6, v0
	v_mov_b32_e32 v7, v0
	v_readfirstlane_b32 s98, v175
	s_nop 3
	s_lshr_b32 s98, s98, 6
	s_mul_i32 s98, s98, 0x4200
	v_lshrrev_b32_e32 v185, 5, v174
	v_lshlrev_b32_e32 v185, 12, v185
	v_and_b32_e32 v186, 31, v174
	v_lshl_add_u32 v176, v186, 4, v185
	v_add_u32_e32 v177, 0x2000, v176
	v_add_u32_e32 v178, 0x4000, v176
	v_add_u32_e32 v179, 0x6000, v176
	v_add_u32_e32 v180, 0x8000, v176
	v_add_u32_e32 v181, 0xa000, v176
	v_add_u32_e32 v182, 0xc000, v176
	v_add_u32_e32 v183, 0xe000, v176
	v_and_b32_e32 v185, 15, v174
	v_lshrrev_b32_e32 v186, 1, v185
	v_mul_u32_u24_e32 v186, 0x420, v186
	v_and_b32_e32 v185, 1, v185
	v_lshl_add_u32 v186, v185, 9, v186
	v_lshrrev_b32_e32 v185, 4, v174
	v_lshl_add_u32 v186, v185, 4, v186
	v_add_u32_e32 v184, s98, v186
	s_lshl_b32 s100, s20, 12
	s_add_u32 s100, s100, 0x6800000
	s_add_u32 s100, s80, s100
	s_addc_u32 s101, s81, 0
	s_mov_b32 s99, 0
	s_add_i32 m0, s98, 0
	s_nop 0
	global_load_lds_dwordx4 v176, s[100:101]
	s_add_i32 m0, s98, 1056
	s_nop 0
	global_load_lds_dwordx4 v177, s[100:101]
	s_add_i32 m0, s98, 2112
	s_nop 0
	global_load_lds_dwordx4 v178, s[100:101]
	s_add_i32 m0, s98, 3168
	s_nop 0
	global_load_lds_dwordx4 v179, s[100:101]
	s_add_i32 m0, s98, 4224
	s_nop 0
	global_load_lds_dwordx4 v180, s[100:101]
	s_add_i32 m0, s98, 5280
	s_nop 0
	global_load_lds_dwordx4 v181, s[100:101]
	s_add_i32 m0, s98, 6336
	s_nop 0
	global_load_lds_dwordx4 v182, s[100:101]
	s_add_i32 m0, s98, 7392
	s_nop 0
	global_load_lds_dwordx4 v183, s[100:101]
	v_add_co_u32_e32 v12, vcc, s99, v112
	s_nop 1
	v_addc_co_u32_e32 v13, vcc, 0, v113, vcc
	global_load_dwordx4 v[48:51], v[12:13], off
	global_load_dwordx4 v[52:55], v[12:13], off offset:64
	global_load_dwordx4 v[56:59], v[12:13], off offset:128
	global_load_dwordx4 v[60:63], v[12:13], off offset:192
	global_load_dwordx4 v[64:67], v[12:13], off offset:256
	global_load_dwordx4 v[68:71], v[12:13], off offset:320
	global_load_dwordx4 v[72:75], v[12:13], off offset:384
	global_load_dwordx4 v[76:79], v[12:13], off offset:448
	s_add_u32 s100, s100, 0x200
	s_addc_u32 s101, s101, 0
	s_add_u32 s99, s99, 0x200
; __device__ __forceinline__ void phase_h1(const Args& a, int lane, int wave) {
;     ...
;         asm volatile("s_waitcnt vmcnt(0)" ::: "memory");
;         { const int r16 = lane & 15, q4 = lane >> 4;
;           const bf16* hrow = H + (size_t)(m0 + r16) * D + 8 * q4; const bf16* wrow = (const bf16*)(a.ws + WS_WIN) + (size_t)(NIN + r16) * D + 8 * q4;
;           f32x4 acc0 = (f32x4){0.f, 0.f, 0.f, 0.f}, acc1 = acc0;
;           bf16x8 af[8], bf[8], an[8], bn[8];
; #pragma unroll
;           for (int i = 0; i < 8; ++i) { af[i] = *(const bf16x8*)(hrow + 32 * i); bf[i] = *(const bf16x8*)(wrow + 32 * i); }
;           for (int ks = 0; ks < 64; ks += 8) {
;               const int kn = ks + 8 < 64 ? ks + 8 : ks;
; #pragma unroll
;               for (int i = 0; i < 8; ++i) { an[i] = *(const bf16x8*)(hrow + 32 * (kn + i)); bn[i] = *(const bf16x8*)(wrow + 32 * (kn + i)); }
; #pragma unroll
;               for (int i = 0; i < 8; i += 2) { acc0 = __builtin_amdgcn_mfma_f32_16x16x32_bf16(af[i], bf[i], acc0, 0, 0, 0); acc1 = __builtin_amdgcn_mfma_f32_16x16x32_bf16(af[i + 1], bf[i + 1], acc1, 0, 0, 0); }
; #pragma unroll
;               for (int i = 0; i < 8; ++i) { af[i] = an[i]; bf[i] = bn[i]; } }
;           float* alr = (float*)(a.ws + WS_ALR);
; #pragma unroll
;           for (int x = 0; x < 4; ++x) alr[(size_t)(m0 + 4 * q4 + x) * 16 + r16] = acc0[x] + acc1[x]; }
.Lalrd_loop:
	s_add_i32 m0, s98, 8448
	s_nop 0
	global_load_lds_dwordx4 v176, s[100:101]
	s_add_i32 m0, s98, 9504
	s_nop 0
	global_load_lds_dwordx4 v177, s[100:101]
	s_add_i32 m0, s98, 10560
	s_nop 0
	global_load_lds_dwordx4 v178, s[100:101]
	s_add_i32 m0, s98, 11616
	s_nop 0
	global_load_lds_dwordx4 v179, s[100:101]
	s_add_i32 m0, s98, 12672
	s_nop 0
	global_load_lds_dwordx4 v180, s[100:101]
	s_add_i32 m0, s98, 13728
	s_nop 0
	global_load_lds_dwordx4 v181, s[100:101]
	s_add_i32 m0, s98, 14784
	s_nop 0
	global_load_lds_dwordx4 v182, s[100:101]
	s_add_i32 m0, s98, 15840
	s_nop 0
	global_load_lds_dwordx4 v183, s[100:101]
	v_add_co_u32_e32 v12, vcc, s99, v112
	s_nop 1
	v_addc_co_u32_e32 v13, vcc, 0, v113, vcc
	global_load_dwordx4 v[124:127], v[12:13], off
	global_load_dwordx4 v[128:131], v[12:13], off offset:64
	global_load_dwordx4 v[132:135], v[12:13], off offset:128
	global_load_dwordx4 v[136:139], v[12:13], off offset:192
	global_load_dwordx4 v[140:143], v[12:13], off offset:256
	global_load_dwordx4 v[144:147], v[12:13], off offset:320
	global_load_dwordx4 v[148:151], v[12:13], off offset:384
	global_load_dwordx4 v[152:155], v[12:13], off offset:448
	s_add_u32 s100, s100, 0x200
	s_addc_u32 s101, s101, 0
	s_add_u32 s99, s99, 0x200
	s_waitcnt vmcnt(16)
	ds_read_b128 v[16:19], v184 offset:0
	ds_read_b128 v[20:23], v184 offset:64
	ds_read_b128 v[24:27], v184 offset:128
	ds_read_b128 v[28:31], v184 offset:192
	ds_read_b128 v[32:35], v184 offset:256
	ds_read_b128 v[36:39], v184 offset:320
	ds_read_b128 v[40:43], v184 offset:384
	ds_read_b128 v[44:47], v184 offset:448
	s_waitcnt lgkmcnt(0)
	v_mfma_f32_16x16x32_bf16 v[4:7], v[16:19], v[48:51], v[4:7]
	v_mfma_f32_16x16x32_bf16 v[0:3], v[20:23], v[52:55], v[0:3]
	v_mfma_f32_16x16x32_bf16 v[4:7], v[24:27], v[56:59], v[4:7]
	v_mfma_f32_16x16x32_bf16 v[0:3], v[28:31], v[60:63], v[0:3]
	v_mfma_f32_16x16x32_bf16 v[4:7], v[32:35], v[64:67], v[4:7]
	v_mfma_f32_16x16x32_bf16 v[0:3], v[36:39], v[68:71], v[0:3]
	v_mfma_f32_16x16x32_bf16 v[4:7], v[40:43], v[72:75], v[4:7]
	v_mfma_f32_16x16x32_bf16 v[0:3], v[44:47], v[76:79], v[0:3]
	s_cmpk_lt_u32 s99, 0x1000
	s_cbranch_scc0 .Lalrd_last
	s_add_i32 m0, s98, 0
	s_nop 0
	global_load_lds_dwordx4 v176, s[100:101]
	s_add_i32 m0, s98, 1056
	s_nop 0
	global_load_lds_dwordx4 v177, s[100:101]
	s_add_i32 m0, s98, 2112
	s_nop 0
	global_load_lds_dwordx4 v178, s[100:101]
	s_add_i32 m0, s98, 3168
	s_nop 0
	global_load_lds_dwordx4 v179, s[100:101]
	s_add_i32 m0, s98, 4224
	s_nop 0
	global_load_lds_dwordx4 v180, s[100:101]
	s_add_i32 m0, s98, 5280
	s_nop 0
	global_load_lds_dwordx4 v181, s[100:101]
	s_add_i32 m0, s98, 6336
	s_nop 0
	global_load_lds_dwordx4 v182, s[100:101]
	s_add_i32 m0, s98, 7392
	s_nop 0
	global_load_lds_dwordx4 v183, s[100:101]
	v_add_co_u32_e32 v12, vcc, s99, v112
	s_nop 1
	v_addc_co_u32_e32 v13, vcc, 0, v113, vcc
	global_load_dwordx4 v[48:51], v[12:13], off
	global_load_dwordx4 v[52:55], v[12:13], off offset:64
	global_load_dwordx4 v[56:59], v[12:13], off offset:128
	global_load_dwordx4 v[60:63], v[12:13], off offset:192
	global_load_dwordx4 v[64:67], v[12:13], off offset:256
	global_load_dwordx4 v[68:71], v[12:13], off offset:320
	global_load_dwordx4 v[72:75], v[12:13], off offset:384
	global_load_dwordx4 v[76:79], v[12:13], off offset:448
	s_add_u32 s100, s100, 0x200
	s_addc_u32 s101, s101, 0
	s_add_u32 s99, s99, 0x200
	s_waitcnt vmcnt(16)
	ds_read_b128 v[16:19], v184 offset:8448
	ds_read_b128 v[20:23], v184 offset:8512
	ds_read_b128 v[24:27], v184 offset:8576
	ds_read_b128 v[28:31], v184 offset:8640
	ds_read_b128 v[32:35], v184 offset:8704
	ds_read_b128 v[36:39], v184 offset:8768
	ds_read_b128 v[40:43], v184 offset:8832
	ds_read_b128 v[44:47], v184 offset:8896
	s_waitcnt lgkmcnt(0)
	v_mfma_f32_16x16x32_bf16 v[4:7], v[16:19], v[124:127], v[4:7]
	v_mfma_f32_16x16x32_bf16 v[0:3], v[20:23], v[128:131], v[0:3]
	v_mfma_f32_16x16x32_bf16 v[4:7], v[24:27], v[132:135], v[4:7]
	v_mfma_f32_16x16x32_bf16 v[0:3], v[28:31], v[136:139], v[0:3]
	v_mfma_f32_16x16x32_bf16 v[4:7], v[32:35], v[140:143], v[4:7]
	v_mfma_f32_16x16x32_bf16 v[0:3], v[36:39], v[144:147], v[0:3]
	v_mfma_f32_16x16x32_bf16 v[4:7], v[40:43], v[148:151], v[4:7]
	v_mfma_f32_16x16x32_bf16 v[0:3], v[44:47], v[152:155], v[0:3]
	s_branch .Lalrd_loop
.Lalrd_last:
	s_waitcnt vmcnt(0)
	ds_read_b128 v[16:19], v184 offset:8448
	ds_read_b128 v[20:23], v184 offset:8512
	ds_read_b128 v[24:27], v184 offset:8576
	ds_read_b128 v[28:31], v184 offset:8640
	ds_read_b128 v[32:35], v184 offset:8704
	ds_read_b128 v[36:39], v184 offset:8768
	ds_read_b128 v[40:43], v184 offset:8832
	ds_read_b128 v[44:47], v184 offset:8896
	s_waitcnt lgkmcnt(0)
	v_mfma_f32_16x16x32_bf16 v[4:7], v[16:19], v[124:127], v[4:7]
	v_mfma_f32_16x16x32_bf16 v[0:3], v[20:23], v[128:131], v[0:3]
	v_mfma_f32_16x16x32_bf16 v[4:7], v[24:27], v[132:135], v[4:7]
	v_mfma_f32_16x16x32_bf16 v[0:3], v[28:31], v[136:139], v[0:3]
	v_mfma_f32_16x16x32_bf16 v[4:7], v[32:35], v[140:143], v[4:7]
	v_mfma_f32_16x16x32_bf16 v[0:3], v[36:39], v[144:147], v[0:3]
	v_mfma_f32_16x16x32_bf16 v[4:7], v[40:43], v[148:151], v[4:7]
	v_mfma_f32_16x16x32_bf16 v[0:3], v[44:47], v[152:155], v[0:3]
	s_nop 7
	s_nop 3
	v_or_b32_e32 v8, s20, v159
	v_ashrrev_i32_e32 v9, 31, v8
	v_lshlrev_b64 v[10:11], 6, v[8:9]
	s_nop 1
	v_add_f32_e32 v0, v4, v0
	v_lshl_add_u64 v[10:11], v[114:115], 0, v[10:11]
	global_store_dword v[10:11], v0, off
	v_or_b32_e32 v0, 1, v8
	v_add_f32_e32 v4, v5, v1
	v_ashrrev_i32_e32 v1, 31, v0
	v_lshlrev_b64 v[0:1], 6, v[0:1]
	v_lshl_add_u64 v[0:1], v[114:115], 0, v[0:1]
	global_store_dword v[0:1], v4, off
	v_or_b32_e32 v0, 2, v8
	v_ashrrev_i32_e32 v1, 31, v0
	v_lshlrev_b64 v[0:1], 6, v[0:1]
	v_add_f32_e32 v2, v6, v2
	v_lshl_add_u64 v[0:1], v[114:115], 0, v[0:1]
	global_store_dword v[0:1], v2, off
	v_or_b32_e32 v0, 3, v8
	v_ashrrev_i32_e32 v1, 31, v0
	v_lshlrev_b64 v[0:1], 6, v[0:1]
	s_add_i32 s26, s26, s29
	s_add_i32 s30, s30, s31
	s_add_i32 s8, s8, s31
	v_add_f32_e32 v2, v7, v3
	v_lshl_add_u64 v[0:1], v[114:115], 0, v[0:1]
	s_cmpk_gt_i32 s26, 0x7ff
	v_add_u32_e32 v116, s31, v116
	global_store_dword v[0:1], v2, off
	s_cbranch_scc0 .LBB0_146
